# P7 prologue: accumulator initialisation waits only for the residual loads (vmcnt(8)), the first operand pieces stay in flight
# baseline (speedup 1.0000x reference)
; #define PG8_STAGE(bufoff, gbase, voff) do { _Pragma("unroll") for (int _i = 0; _i < 2; ++_i) \
;         __builtin_amdgcn_global_load_lds((const unsigned*)((const char*)(gbase) + (voff)[_i]), (PG8_LAS unsigned*)(lds + (bufoff) + ldsw + _i * 8192), 16, 0, 0); } while (0)
; #define PG8_WAIT_V(n) asm volatile("s_waitcnt vmcnt(" #n ")" ::: "memory")
; #define PG8_BAR __builtin_amdgcn_s_barrier()
;     __device__ __forceinline__ void init(f32x4 (&acc)[2][2][4][2], const Unit& u, int wr, int wc, int fr, int fq) const {
;     ...
;             for (int h = 0; h < 2; ++h) { const f32x4 gv = *(const f32x4*)(G + col0 + bj * HALF + 4 * h); gi[bj][h] = (f32x4){1.f / gv[0], 1.f / gv[1], 1.f / gv[2], 1.f / gv[3]}; }
; #pragma unroll
;         for (int ai = 0; ai < 2; ++ai)
; #pragma unroll
;             for (int m = 0; m < 4; ++m) { const int row = row0 + ai * HALF + m * 16; const size_t off = (size_t)row * ldc + col0; const float ri = RINV[row];
; #pragma unroll
;                 for (int bj = 0; bj < 2; ++bj) { const u32x4 w = *(const u32x4*)(XN + off + bj * HALF);
;                     const f32x4 x0 = (f32x4){__builtin_bit_cast(float, w.x << 16), __builtin_bit_cast(float, w.x & 0xffff0000u), __builtin_bit_cast(float, w.y << 16), __builtin_bit_cast(float, w.y & 0xffff0000u)};
;                     const f32x4 x1 = (f32x4){__builtin_bit_cast(float, w.z << 16), __builtin_bit_cast(float, w.z & 0xffff0000u), __builtin_bit_cast(float, w.w << 16), __builtin_bit_cast(float, w.w & 0xffff0000u)};
;                     acc[ai][bj][m][0] = x0 * gi[bj][0] * ri; acc[ai][bj][m][1] = x1 * gi[bj][1] * ri; } }
; template <class Epi, class Sched, bool STAMP = false>
; __device__ __forceinline__ void gemm_phase(PG8_LAS unsigned char* lds, const Gemm g, const Sched& S, const Epi& E, unsigned long long* stamps) {
;     ...
;     PG8_STAGE(PG8_SB(0, 0), cB, voffB); PG8_STAGE(PG8_SA(0, 0), cA, voffA); PG8_STAGE(PG8_SB(0, 1), cB + hstep, voffB); PG8_STAGE(PG8_SA(0, 1), cA + hstep, voffA);
;     if (wr == 1) PG8_BAR;
;     PG8_WAIT_V(4); PG8_BAR;
;     PG8_STAGE(PG8_SB(1, 0), cB + kstep, voffB); PG8_STAGE(PG8_SA(1, 0), cA + kstep, voffA); PG8_STAGE(PG8_SB(1, 1), cB + hstep + kstep, voffB);
;     PG8_WAIT_V(6); PG8_BAR;
.LBB0_507:
	s_waitcnt vmcnt(8)
	v_div_scale_f32 v39, s[16:17], v30, v30, 1.0
	v_rcp_f32_e32 v41, v39
	v_div_scale_f32 v47, vcc, 1.0, v30, 1.0
	s_mov_b64 s[30:31], 0x80
	v_fma_f32 v48, -v39, v41, 1.0
	v_fmac_f32_e32 v41, v48, v41
	v_mul_f32_e32 v48, v47, v41
	v_fma_f32 v49, -v39, v48, v47
	v_fmac_f32_e32 v48, v49, v41
	v_fma_f32 v39, -v39, v48, v47
	v_div_scale_f32 v47, s[16:17], v31, v31, 1.0
	v_rcp_f32_e32 v49, v47
	v_div_fmas_f32 v39, v39, v41, v48
	v_div_fixup_f32 v122, v39, v30, 1.0
	s_add_i32 m0, s48, 0x18000
	v_fma_f32 v30, -v47, v49, 1.0
	v_fmac_f32_e32 v49, v30, v49
	v_div_scale_f32 v30, vcc, 1.0, v31, 1.0
	v_mul_f32_e32 v39, v30, v49
	v_fma_f32 v41, -v47, v39, v30
	v_fmac_f32_e32 v39, v41, v49
	v_div_scale_f32 v41, s[16:17], v32, v32, 1.0
	v_fma_f32 v30, -v47, v39, v30
	v_rcp_f32_e32 v47, v41
	v_div_fmas_f32 v30, v30, v49, v39
	v_div_fixup_f32 v123, v30, v31, 1.0
	v_lshl_add_u64 v[138:139], v[138:139], 0, s[30:31]
	v_fma_f32 v30, -v41, v47, 1.0
	v_fmac_f32_e32 v47, v30, v47
	v_div_scale_f32 v30, vcc, 1.0, v32, 1.0
	v_mul_f32_e32 v31, v30, v47
	v_fma_f32 v39, -v41, v31, v30
	v_fmac_f32_e32 v31, v39, v47
	v_div_scale_f32 v39, s[16:17], v33, v33, 1.0
	v_fma_f32 v30, -v41, v31, v30
	v_rcp_f32_e32 v41, v39
	v_div_fmas_f32 v30, v30, v47, v31
	v_div_fixup_f32 v140, v30, v32, 1.0
	s_lshl_b32 s5, s12, 13
	v_fma_f32 v30, -v39, v41, 1.0
	v_fmac_f32_e32 v41, v30, v41
	v_div_scale_f32 v30, vcc, 1.0, v33, 1.0
	v_mul_f32_e32 v31, v30, v41
	v_fma_f32 v32, -v39, v31, v30
	v_fmac_f32_e32 v31, v32, v41
	v_div_scale_f32 v32, s[16:17], v22, v22, 1.0
	v_fma_f32 v30, -v39, v31, v30
	v_rcp_f32_e32 v39, v32
	v_div_fmas_f32 v30, v30, v41, v31
	v_div_fixup_f32 v141, v30, v33, 1.0
	s_lshl_b32 s15, s10, 7
	v_fma_f32 v30, -v32, v39, 1.0
	v_fmac_f32_e32 v39, v30, v39
	v_div_scale_f32 v30, vcc, 1.0, v22, 1.0
	v_mul_f32_e32 v31, v30, v39
	v_fma_f32 v33, -v32, v31, v30
	v_fmac_f32_e32 v31, v33, v39
	v_fma_f32 v30, -v32, v31, v30
	v_div_scale_f32 v32, s[16:17], v23, v23, 1.0
	v_rcp_f32_e32 v33, v32
	v_div_fmas_f32 v30, v30, v39, v31
	v_div_fixup_f32 v142, v30, v22, 1.0
	s_waitcnt vmcnt(4)
	v_fma_f32 v22, -v32, v33, 1.0
	v_fmac_f32_e32 v33, v22, v33
	v_div_scale_f32 v22, vcc, 1.0, v23, 1.0
	v_mul_f32_e32 v30, v22, v33
	v_fma_f32 v31, -v32, v30, v22
	v_fmac_f32_e32 v30, v31, v33
	v_div_scale_f32 v31, s[16:17], v24, v24, 1.0
	v_fma_f32 v22, -v32, v30, v22
	v_rcp_f32_e32 v32, v31
	v_div_fmas_f32 v22, v22, v33, v30
	v_div_fixup_f32 v143, v22, v23, 1.0
	s_barrier
	v_fma_f32 v22, -v31, v32, 1.0
	v_fmac_f32_e32 v32, v22, v32
	v_div_scale_f32 v22, vcc, 1.0, v24, 1.0
	v_mul_f32_e32 v23, v22, v32
	v_fma_f32 v30, -v31, v23, v22
	v_fmac_f32_e32 v23, v30, v32
	v_div_scale_f32 v30, s[16:17], v25, v25, 1.0
	v_fma_f32 v22, -v31, v23, v22
	v_rcp_f32_e32 v31, v30
	v_div_fmas_f32 v22, v22, v32, v23
	v_div_fixup_f32 v144, v22, v24, 1.0
	global_load_lds_dwordx4 v[138:139], off
	v_fma_f32 v22, -v30, v31, 1.0
	v_fmac_f32_e32 v31, v22, v31
	v_div_scale_f32 v22, vcc, 1.0, v25, 1.0
	v_mul_f32_e32 v23, v22, v31
	v_fma_f32 v24, -v30, v23, v22
	v_fmac_f32_e32 v23, v24, v31
	v_div_scale_f32 v24, s[16:17], v14, v14, 1.0
	v_fma_f32 v22, -v30, v23, v22
	v_rcp_f32_e32 v30, v24
	v_div_fmas_f32 v22, v22, v31, v23
	v_div_fixup_f32 v145, v22, v25, 1.0
	v_lshl_add_u64 v[128:129], v[128:129], 0, s[30:31]
	v_fma_f32 v22, -v24, v30, 1.0
	v_fmac_f32_e32 v30, v22, v30
	v_div_scale_f32 v22, vcc, 1.0, v14, 1.0
	v_mul_f32_e32 v23, v22, v30
	v_fma_f32 v25, -v24, v23, v22
	v_fmac_f32_e32 v23, v25, v30
	v_fma_f32 v22, -v24, v23, v22
	v_div_scale_f32 v24, s[16:17], v15, v15, 1.0
	v_rcp_f32_e32 v25, v24
	v_div_fmas_f32 v22, v22, v30, v23
	v_div_fixup_f32 v146, v22, v14, 1.0
	s_add_i32 m0, s48, 0x1a000
	v_fma_f32 v14, -v24, v25, 1.0
	v_fmac_f32_e32 v25, v14, v25
	v_div_scale_f32 v14, vcc, 1.0, v15, 1.0
	v_mul_f32_e32 v22, v14, v25
	v_fma_f32 v23, -v24, v22, v14
	v_fmac_f32_e32 v22, v23, v25
	v_div_scale_f32 v23, s[16:17], v16, v16, 1.0
	v_fma_f32 v14, -v24, v22, v14
	v_rcp_f32_e32 v24, v23
	v_div_fmas_f32 v14, v14, v25, v22
	v_div_fixup_f32 v147, v14, v15, 1.0
	s_add_i32 s55, s48, 0x8000
	v_fma_f32 v14, -v23, v24, 1.0
	v_fmac_f32_e32 v24, v14, v24
	v_div_scale_f32 v14, vcc, 1.0, v16, 1.0
	v_mul_f32_e32 v15, v14, v24
	v_fma_f32 v22, -v23, v15, v14
	v_fmac_f32_e32 v15, v22, v24
	v_div_scale_f32 v22, s[16:17], v17, v17, 1.0
	v_fma_f32 v14, -v23, v15, v14
	v_rcp_f32_e32 v23, v22
	v_div_fmas_f32 v14, v14, v24, v15
	v_div_fixup_f32 v148, v14, v16, 1.0
	s_add_i32 s56, s48, 0xa000
	v_fma_f32 v14, -v22, v23, 1.0
	v_fmac_f32_e32 v23, v14, v23
	v_div_scale_f32 v14, vcc, 1.0, v17, 1.0
	v_mul_f32_e32 v15, v14, v23
	v_fma_f32 v16, -v22, v15, v14
	v_fmac_f32_e32 v15, v16, v23
	v_div_scale_f32 v16, s[16:17], v2, v2, 1.0
	v_fma_f32 v14, -v22, v15, v14
	v_rcp_f32_e32 v22, v16
	global_load_lds_dwordx4 v[128:129], off
	v_lshl_add_u64 v[124:125], v[124:125], 0, s[30:31]
	s_mov_b32 m0, s55
	s_add_u32 s12, s6, 0x40080
	global_load_lds_dwordx4 v[124:125], off
	v_lshl_add_u64 v[112:113], v[112:113], 0, s[30:31]
	s_mov_b32 m0, s56
	s_addc_u32 s13, s7, 0
	v_div_fmas_f32 v14, v14, v23, v15
	global_load_lds_dwordx4 v[112:113], off
	s_add_i32 m0, s48, 0x1c000
	v_lshl_add_u64 v[112:113], s[12:13], 0, v[132:133]
	v_div_fixup_f32 v149, v14, v17, 1.0
	v_fma_f32 v14, -v16, v22, 1.0
	global_load_lds_dwordx4 v[112:113], off
	v_lshl_add_u64 v[112:113], s[12:13], 0, v[136:137]
	s_add_i32 m0, s48, 0x1e000
	v_fmac_f32_e32 v22, v14, v22
	v_div_scale_f32 v14, vcc, 1.0, v2, 1.0
	global_load_lds_dwordx4 v[112:113], off
	v_mul_f32_e32 v15, v14, v22
	v_fma_f32 v17, -v16, v15, v14
	v_fmac_f32_e32 v15, v17, v22
	v_fma_f32 v14, -v16, v15, v14
;     __device__ __forceinline__ void init(f32x4 (&acc)[2][2][4][2], const Unit& u, int wr, int wc, int fr, int fq) const {
;     ...
;             for (int h = 0; h < 2; ++h) { const f32x4 gv = *(const f32x4*)(G + col0 + bj * HALF + 4 * h); gi[bj][h] = (f32x4){1.f / gv[0], 1.f / gv[1], 1.f / gv[2], 1.f / gv[3]}; }
; #pragma unroll
;         for (int ai = 0; ai < 2; ++ai)
; #pragma unroll
;             for (int m = 0; m < 4; ++m) { const int row = row0 + ai * HALF + m * 16; const size_t off = (size_t)row * ldc + col0; const float ri = RINV[row];
; #pragma unroll
;                 for (int bj = 0; bj < 2; ++bj) { const u32x4 w = *(const u32x4*)(XN + off + bj * HALF);
;                     const f32x4 x0 = (f32x4){__builtin_bit_cast(float, w.x << 16), __builtin_bit_cast(float, w.x & 0xffff0000u), __builtin_bit_cast(float, w.y << 16), __builtin_bit_cast(float, w.y & 0xffff0000u)};
;                     const f32x4 x1 = (f32x4){__builtin_bit_cast(float, w.z << 16), __builtin_bit_cast(float, w.z & 0xffff0000u), __builtin_bit_cast(float, w.w << 16), __builtin_bit_cast(float, w.w & 0xffff0000u)};
;                     acc[ai][bj][m][0] = x0 * gi[bj][0] * ri; acc[ai][bj][m][1] = x1 * gi[bj][1] * ri; } }
	v_div_scale_f32 v16, s[16:17], v3, v3, 1.0
	v_rcp_f32_e32 v17, v16
	v_div_fmas_f32 v14, v14, v22, v15
	v_div_fixup_f32 v150, v14, v2, 1.0
	v_lshlrev_b32_e32 v22, 16, v13
	v_fma_f32 v2, -v16, v17, 1.0
	v_fmac_f32_e32 v17, v2, v17
	v_div_scale_f32 v2, vcc, 1.0, v3, 1.0
	v_mul_f32_e32 v14, v2, v17
	v_fma_f32 v15, -v16, v14, v2
	v_fmac_f32_e32 v14, v15, v17
	v_div_scale_f32 v15, s[16:17], v4, v4, 1.0
	v_fma_f32 v2, -v16, v14, v2
	v_rcp_f32_e32 v16, v15
	v_div_fmas_f32 v2, v2, v17, v14
	v_div_fixup_f32 v151, v2, v3, 1.0
	v_and_b32_e32 v17, 0xffff0000, v12
	v_fma_f32 v2, -v15, v16, 1.0
	v_fmac_f32_e32 v16, v2, v16
	v_div_scale_f32 v2, vcc, 1.0, v4, 1.0
	v_mul_f32_e32 v3, v2, v16
	v_fma_f32 v14, -v15, v3, v2
	v_fmac_f32_e32 v3, v14, v16
	v_div_scale_f32 v14, s[16:17], v5, v5, 1.0
	v_fma_f32 v2, -v15, v3, v2
	v_rcp_f32_e32 v15, v14
	v_div_fmas_f32 v2, v2, v16, v3
	v_div_fixup_f32 v152, v2, v4, 1.0
	v_lshlrev_b32_e32 v16, 16, v12
	v_fma_f32 v2, -v14, v15, 1.0
	v_fmac_f32_e32 v15, v2, v15
	v_div_scale_f32 v2, vcc, 1.0, v5, 1.0
	v_mul_f32_e32 v3, v2, v15
	v_fma_f32 v4, -v14, v3, v2
	v_fmac_f32_e32 v3, v4, v15
	v_fma_f32 v2, -v14, v3, v2
	v_div_fmas_f32 v2, v2, v15, v3
	v_lshlrev_b32_e32 v14, 16, v10
	v_and_b32_e32 v15, 0xffff0000, v10
	v_lshlrev_b32_e32 v10, 16, v11
	v_and_b32_e32 v11, 0xffff0000, v11
	v_div_fixup_f32 v153, v2, v5, 1.0
	v_and_b32_e32 v23, 0xffff0000, v13
	v_pk_mul_f32 v[14:15], v[146:147], v[14:15]
	v_pk_mul_f32 v[10:11], v[148:149], v[10:11]
	v_lshlrev_b32_e32 v2, 16, v6
	v_pk_mul_f32 v[12:13], v[40:41], v[10:11] op_sel_hi:[0,1]
	v_pk_mul_f32 v[10:11], v[40:41], v[14:15] op_sel_hi:[0,1]
	v_pk_mul_f32 v[14:15], v[150:151], v[16:17]
	v_pk_mul_f32 v[16:17], v[152:153], v[22:23]
	v_lshlrev_b32_e32 v22, 16, v18
	v_and_b32_e32 v23, 0xffff0000, v18
	v_lshlrev_b32_e32 v18, 16, v19
	v_and_b32_e32 v19, 0xffff0000, v19
	v_and_b32_e32 v3, 0xffff0000, v6
	v_lshlrev_b32_e32 v4, 16, v7
	v_and_b32_e32 v5, 0xffff0000, v7
	v_lshlrev_b32_e32 v6, 16, v8
	v_and_b32_e32 v7, 0xffff0000, v8
	v_lshlrev_b32_e32 v8, 16, v9
	v_and_b32_e32 v9, 0xffff0000, v9
	v_lshlrev_b32_e32 v24, 16, v20
	v_and_b32_e32 v25, 0xffff0000, v20
	v_lshlrev_b32_e32 v30, 16, v21
	v_and_b32_e32 v31, 0xffff0000, v21
	v_pk_mul_f32 v[22:23], v[122:123], v[22:23]
	v_pk_mul_f32 v[18:19], v[140:141], v[18:19]
	v_pk_mul_f32 v[2:3], v[122:123], v[2:3]
	v_pk_mul_f32 v[4:5], v[140:141], v[4:5]
	v_pk_mul_f32 v[6:7], v[142:143], v[6:7]
	v_pk_mul_f32 v[8:9], v[144:145], v[8:9]
	v_pk_mul_f32 v[20:21], v[38:39], v[18:19] op_sel_hi:[0,1]
	v_pk_mul_f32 v[18:19], v[38:39], v[22:23] op_sel_hi:[0,1]
	v_pk_mul_f32 v[22:23], v[142:143], v[24:25]
	v_pk_mul_f32 v[24:25], v[144:145], v[30:31]
	v_lshlrev_b32_e32 v30, 16, v26
	v_and_b32_e32 v31, 0xffff0000, v26
	v_lshlrev_b32_e32 v26, 16, v27
	v_and_b32_e32 v27, 0xffff0000, v27
	v_pk_mul_f32 v[4:5], v[40:41], v[4:5] op_sel_hi:[0,1]
	v_pk_mul_f32 v[2:3], v[40:41], v[2:3] op_sel_hi:[0,1]
	v_pk_mul_f32 v[8:9], v[40:41], v[8:9] op_sel_hi:[0,1]
	v_pk_mul_f32 v[6:7], v[40:41], v[6:7] op_sel_hi:[0,1]
	v_pk_mul_f32 v[16:17], v[40:41], v[16:17] op_sel_hi:[0,1]
	v_pk_mul_f32 v[14:15], v[40:41], v[14:15] op_sel_hi:[0,1]
	v_lshlrev_b32_e32 v32, 16, v28
	v_and_b32_e32 v33, 0xffff0000, v28
	v_lshlrev_b32_e32 v40, 16, v29
	v_and_b32_e32 v41, 0xffff0000, v29
	v_pk_mul_f32 v[30:31], v[146:147], v[30:31]
	v_pk_mul_f32 v[26:27], v[148:149], v[26:27]
	v_pk_mul_f32 v[24:25], v[38:39], v[24:25] op_sel_hi:[0,1]
	v_pk_mul_f32 v[28:29], v[38:39], v[26:27] op_sel_hi:[0,1]
	v_pk_mul_f32 v[26:27], v[38:39], v[30:31] op_sel_hi:[0,1]
	v_pk_mul_f32 v[30:31], v[150:151], v[32:33]
	v_pk_mul_f32 v[32:33], v[152:153], v[40:41]
	v_pk_mul_f32 v[22:23], v[38:39], v[22:23] op_sel_hi:[0,1]
	v_pk_mul_f32 v[32:33], v[38:39], v[32:33] op_sel_hi:[0,1]
	v_pk_mul_f32 v[30:31], v[38:39], v[30:31] op_sel_hi:[0,1]
	v_lshlrev_b32_e32 v38, 16, v34
	v_and_b32_e32 v39, 0xffff0000, v34
	v_lshlrev_b32_e32 v34, 16, v35
	v_and_b32_e32 v35, 0xffff0000, v35
	v_lshlrev_b32_e32 v40, 16, v36
	v_and_b32_e32 v41, 0xffff0000, v36
	v_lshlrev_b32_e32 v48, 16, v37
	v_and_b32_e32 v49, 0xffff0000, v37
	v_pk_mul_f32 v[38:39], v[122:123], v[38:39]
	v_pk_mul_f32 v[34:35], v[140:141], v[34:35]
	v_lshlrev_b32_e32 v54, 16, v44
	v_pk_mul_f32 v[36:37], v[46:47], v[34:35] op_sel_hi:[0,1]
	v_pk_mul_f32 v[34:35], v[46:47], v[38:39] op_sel_hi:[0,1]
	v_pk_mul_f32 v[38:39], v[142:143], v[40:41]
	v_pk_mul_f32 v[40:41], v[144:145], v[48:49]
	v_lshlrev_b32_e32 v48, 16, v42
	v_and_b32_e32 v49, 0xffff0000, v42
	v_lshlrev_b32_e32 v42, 16, v43
	v_and_b32_e32 v43, 0xffff0000, v43
	v_and_b32_e32 v55, 0xffff0000, v44
	v_lshlrev_b32_e32 v56, 16, v45
	v_and_b32_e32 v57, 0xffff0000, v45
	v_pk_mul_f32 v[48:49], v[146:147], v[48:49]
	v_pk_mul_f32 v[42:43], v[148:149], v[42:43]
	v_pk_mul_f32 v[54:55], v[150:151], v[54:55]
	v_pk_mul_f32 v[44:45], v[46:47], v[42:43] op_sel_hi:[0,1]
	v_pk_mul_f32 v[42:43], v[46:47], v[48:49] op_sel_hi:[0,1]
	v_pk_mul_f32 v[48:49], v[152:153], v[56:57]
	v_pk_mul_f32 v[40:41], v[46:47], v[40:41] op_sel_hi:[0,1]
	v_pk_mul_f32 v[38:39], v[46:47], v[38:39] op_sel_hi:[0,1]
	v_pk_mul_f32 v[48:49], v[46:47], v[48:49] op_sel_hi:[0,1]
	v_pk_mul_f32 v[46:47], v[46:47], v[54:55] op_sel_hi:[0,1]
	v_lshlrev_b32_e32 v54, 16, v50
	v_and_b32_e32 v55, 0xffff0000, v50
	v_lshlrev_b32_e32 v50, 16, v51
	v_and_b32_e32 v51, 0xffff0000, v51
	v_lshlrev_b32_e32 v56, 16, v52
	v_and_b32_e32 v57, 0xffff0000, v52
	v_lshlrev_b32_e32 v64, 16, v53
	v_and_b32_e32 v65, 0xffff0000, v53
	v_pk_mul_f32 v[54:55], v[122:123], v[54:55]
	v_pk_mul_f32 v[50:51], v[140:141], v[50:51]
	v_lshlrev_b32_e32 v70, 16, v60
	v_pk_mul_f32 v[52:53], v[62:63], v[50:51] op_sel_hi:[0,1]
;     __device__ __forceinline__ void init(f32x4 (&acc)[2][2][4][2], const Unit& u, int wr, int wc, int fr, int fq) const {
;     ...
;             for (int m = 0; m < 4; ++m) { const int row = row0 + ai * HALF + m * 16; const size_t off = (size_t)row * ldc + col0; const float ri = RINV[row];
; #pragma unroll
;                 for (int bj = 0; bj < 2; ++bj) { const u32x4 w = *(const u32x4*)(XN + off + bj * HALF);
;                     const f32x4 x0 = (f32x4){__builtin_bit_cast(float, w.x << 16), __builtin_bit_cast(float, w.x & 0xffff0000u), __builtin_bit_cast(float, w.y << 16), __builtin_bit_cast(float, w.y & 0xffff0000u)};
;                     const f32x4 x1 = (f32x4){__builtin_bit_cast(float, w.z << 16), __builtin_bit_cast(float, w.z & 0xffff0000u), __builtin_bit_cast(float, w.w << 16), __builtin_bit_cast(float, w.w & 0xffff0000u)};
;                     acc[ai][bj][m][0] = x0 * gi[bj][0] * ri; acc[ai][bj][m][1] = x1 * gi[bj][1] * ri; } }
	v_pk_mul_f32 v[50:51], v[62:63], v[54:55] op_sel_hi:[0,1]
	v_pk_mul_f32 v[54:55], v[142:143], v[56:57]
	v_pk_mul_f32 v[56:57], v[144:145], v[64:65]
	v_lshlrev_b32_e32 v64, 16, v58
	v_and_b32_e32 v65, 0xffff0000, v58
	v_lshlrev_b32_e32 v58, 16, v59
	v_and_b32_e32 v59, 0xffff0000, v59
	v_and_b32_e32 v71, 0xffff0000, v60
	v_lshlrev_b32_e32 v72, 16, v61
	v_and_b32_e32 v73, 0xffff0000, v61
	v_pk_mul_f32 v[64:65], v[146:147], v[64:65]
	v_pk_mul_f32 v[58:59], v[148:149], v[58:59]
	v_pk_mul_f32 v[70:71], v[150:151], v[70:71]
	v_pk_mul_f32 v[60:61], v[62:63], v[58:59] op_sel_hi:[0,1]
	v_pk_mul_f32 v[58:59], v[62:63], v[64:65] op_sel_hi:[0,1]
	v_pk_mul_f32 v[64:65], v[152:153], v[72:73]
	v_pk_mul_f32 v[56:57], v[62:63], v[56:57] op_sel_hi:[0,1]
	v_pk_mul_f32 v[54:55], v[62:63], v[54:55] op_sel_hi:[0,1]
	v_pk_mul_f32 v[64:65], v[62:63], v[64:65] op_sel_hi:[0,1]
	v_pk_mul_f32 v[62:63], v[62:63], v[70:71] op_sel_hi:[0,1]
	v_lshlrev_b32_e32 v70, 16, v66
	v_and_b32_e32 v71, 0xffff0000, v66
	v_lshlrev_b32_e32 v66, 16, v67
	v_and_b32_e32 v67, 0xffff0000, v67
	v_lshlrev_b32_e32 v72, 16, v68
	v_and_b32_e32 v73, 0xffff0000, v68
	v_lshlrev_b32_e32 v80, 16, v69
	v_and_b32_e32 v81, 0xffff0000, v69
	v_pk_mul_f32 v[70:71], v[122:123], v[70:71]
	v_pk_mul_f32 v[66:67], v[140:141], v[66:67]
	v_lshlrev_b32_e32 v86, 16, v76
	v_pk_mul_f32 v[68:69], v[78:79], v[66:67] op_sel_hi:[0,1]
	v_pk_mul_f32 v[66:67], v[78:79], v[70:71] op_sel_hi:[0,1]
	v_pk_mul_f32 v[70:71], v[142:143], v[72:73]
	v_pk_mul_f32 v[72:73], v[144:145], v[80:81]
	v_lshlrev_b32_e32 v80, 16, v74
	v_and_b32_e32 v81, 0xffff0000, v74
	v_lshlrev_b32_e32 v74, 16, v75
	v_and_b32_e32 v75, 0xffff0000, v75
	v_and_b32_e32 v87, 0xffff0000, v76
	v_lshlrev_b32_e32 v88, 16, v77
	v_and_b32_e32 v89, 0xffff0000, v77
	v_pk_mul_f32 v[80:81], v[146:147], v[80:81]
	v_pk_mul_f32 v[74:75], v[148:149], v[74:75]
	v_pk_mul_f32 v[86:87], v[150:151], v[86:87]
	v_pk_mul_f32 v[76:77], v[78:79], v[74:75] op_sel_hi:[0,1]
	v_pk_mul_f32 v[74:75], v[78:79], v[80:81] op_sel_hi:[0,1]
	v_pk_mul_f32 v[80:81], v[152:153], v[88:89]
	v_pk_mul_f32 v[72:73], v[78:79], v[72:73] op_sel_hi:[0,1]
	v_pk_mul_f32 v[70:71], v[78:79], v[70:71] op_sel_hi:[0,1]
	v_pk_mul_f32 v[80:81], v[78:79], v[80:81] op_sel_hi:[0,1]
	v_pk_mul_f32 v[78:79], v[78:79], v[86:87] op_sel_hi:[0,1]
	v_lshlrev_b32_e32 v86, 16, v82
	v_and_b32_e32 v87, 0xffff0000, v82
	v_lshlrev_b32_e32 v82, 16, v83
	v_and_b32_e32 v83, 0xffff0000, v83
	v_lshlrev_b32_e32 v88, 16, v84
	v_and_b32_e32 v89, 0xffff0000, v84
	v_lshlrev_b32_e32 v96, 16, v85
	v_and_b32_e32 v97, 0xffff0000, v85
	v_pk_mul_f32 v[86:87], v[122:123], v[86:87]
	v_pk_mul_f32 v[82:83], v[140:141], v[82:83]
	v_lshlrev_b32_e32 v102, 16, v92
	v_pk_mul_f32 v[84:85], v[94:95], v[82:83] op_sel_hi:[0,1]
	v_pk_mul_f32 v[82:83], v[94:95], v[86:87] op_sel_hi:[0,1]
	v_pk_mul_f32 v[86:87], v[142:143], v[88:89]
	v_pk_mul_f32 v[88:89], v[144:145], v[96:97]
	v_lshlrev_b32_e32 v96, 16, v90
	v_and_b32_e32 v97, 0xffff0000, v90
	v_lshlrev_b32_e32 v90, 16, v91
	v_and_b32_e32 v91, 0xffff0000, v91
	v_and_b32_e32 v103, 0xffff0000, v92
	v_lshlrev_b32_e32 v104, 16, v93
	v_and_b32_e32 v105, 0xffff0000, v93
	v_pk_mul_f32 v[96:97], v[146:147], v[96:97]
	v_pk_mul_f32 v[90:91], v[148:149], v[90:91]
	v_pk_mul_f32 v[102:103], v[150:151], v[102:103]
	v_pk_mul_f32 v[92:93], v[94:95], v[90:91] op_sel_hi:[0,1]
	v_pk_mul_f32 v[90:91], v[94:95], v[96:97] op_sel_hi:[0,1]
	v_pk_mul_f32 v[96:97], v[152:153], v[104:105]
	v_pk_mul_f32 v[88:89], v[94:95], v[88:89] op_sel_hi:[0,1]
	v_pk_mul_f32 v[86:87], v[94:95], v[86:87] op_sel_hi:[0,1]
	v_pk_mul_f32 v[96:97], v[94:95], v[96:97] op_sel_hi:[0,1]
	v_pk_mul_f32 v[94:95], v[94:95], v[102:103] op_sel_hi:[0,1]
	v_lshlrev_b32_e32 v102, 16, v98
	v_and_b32_e32 v103, 0xffff0000, v98
	v_lshlrev_b32_e32 v98, 16, v99
	v_and_b32_e32 v99, 0xffff0000, v99
	v_lshlrev_b32_e32 v104, 16, v100
	v_and_b32_e32 v105, 0xffff0000, v100
;     __device__ __forceinline__ void init(f32x4 (&acc)[2][2][4][2], const Unit& u, int wr, int wc, int fr, int fq) const {
;     ...
;             for (int m = 0; m < 4; ++m) { const int row = row0 + ai * HALF + m * 16; const size_t off = (size_t)row * ldc + col0; const float ri = RINV[row];
; #pragma unroll
;                 for (int bj = 0; bj < 2; ++bj) { const u32x4 w = *(const u32x4*)(XN + off + bj * HALF);
;                     const f32x4 x0 = (f32x4){__builtin_bit_cast(float, w.x << 16), __builtin_bit_cast(float, w.x & 0xffff0000u), __builtin_bit_cast(float, w.y << 16), __builtin_bit_cast(float, w.y & 0xffff0000u)};
;                     const f32x4 x1 = (f32x4){__builtin_bit_cast(float, w.z << 16), __builtin_bit_cast(float, w.z & 0xffff0000u), __builtin_bit_cast(float, w.w << 16), __builtin_bit_cast(float, w.w & 0xffff0000u)};
;                     acc[ai][bj][m][0] = x0 * gi[bj][0] * ri; acc[ai][bj][m][1] = x1 * gi[bj][1] * ri; } }
; template <class Epi, class Sched, bool STAMP = false>
; __device__ __forceinline__ void gemm_phase(PG8_LAS unsigned char* lds, const Gemm g, const Sched& S, const Epi& E, unsigned long long* stamps) {
;     ...
;     for (int i = 0; i < 2; ++i) { int R, C; stage_rc(tid * 16 + i * 8192, R, C); const int Rb = Epi::PERM ? ((R & ~31) + perm32(R & 31)) : R;
;         voffA[i] = (unsigned)(R * K + C) * 2u; voffB[i] = (unsigned)(Rb * K + C) * 2u; }
;     const size_t kstep = (size_t)(BK * 2);
;     const size_t hstep = (size_t)HALF * K * 2;
;     const size_t tstep = 2 * hstep;
;     const unsigned ldsw = (unsigned)wid * 1024u;
;     const int aoff = lds_byte(wr * 64 + fr, fq * 8), boff = lds_byte(wc * 32 + fr, fq * 8);
	v_lshlrev_b32_e32 v160, 16, v101
	v_and_b32_e32 v161, 0xffff0000, v101
	v_pk_mul_f32 v[102:103], v[122:123], v[102:103]
	v_pk_mul_f32 v[98:99], v[140:141], v[98:99]
	v_lshlrev_b32_e32 v162, 16, v108
	v_pk_mul_f32 v[100:101], v[110:111], v[98:99] op_sel_hi:[0,1]
	v_pk_mul_f32 v[98:99], v[110:111], v[102:103] op_sel_hi:[0,1]
	v_pk_mul_f32 v[102:103], v[142:143], v[104:105]
	v_pk_mul_f32 v[104:105], v[144:145], v[160:161]
	v_lshlrev_b32_e32 v160, 16, v106
	v_and_b32_e32 v161, 0xffff0000, v106
	v_lshlrev_b32_e32 v106, 16, v107
	v_and_b32_e32 v107, 0xffff0000, v107
	v_and_b32_e32 v163, 0xffff0000, v108
	v_lshlrev_b32_e32 v164, 16, v109
	v_and_b32_e32 v165, 0xffff0000, v109
	v_pk_mul_f32 v[112:113], v[146:147], v[160:161]
	v_pk_mul_f32 v[106:107], v[148:149], v[106:107]
	v_pk_mul_f32 v[124:125], v[150:151], v[162:163]
	v_pk_mul_f32 v[108:109], v[110:111], v[106:107] op_sel_hi:[0,1]
	v_pk_mul_f32 v[106:107], v[110:111], v[112:113] op_sel_hi:[0,1]
	v_pk_mul_f32 v[112:113], v[152:153], v[164:165]
	v_pk_mul_f32 v[104:105], v[110:111], v[104:105] op_sel_hi:[0,1]
	v_pk_mul_f32 v[102:103], v[110:111], v[102:103] op_sel_hi:[0,1]
	v_pk_mul_f32 v[112:113], v[110:111], v[112:113] op_sel_hi:[0,1]
	v_pk_mul_f32 v[110:111], v[110:111], v[124:125] op_sel_hi:[0,1]
	v_lshlrev_b32_e32 v124, 16, v114
	v_and_b32_e32 v125, 0xffff0000, v114
	v_lshlrev_b32_e32 v114, 16, v115
	v_and_b32_e32 v115, 0xffff0000, v115
	v_lshlrev_b32_e32 v128, 16, v116
	v_and_b32_e32 v129, 0xffff0000, v116
	v_pk_mul_f32 v[122:123], v[122:123], v[124:125]
	v_pk_mul_f32 v[114:115], v[140:141], v[114:115]
	v_lshlrev_b32_e32 v138, 16, v117
	v_and_b32_e32 v139, 0xffff0000, v117
	v_pk_mul_f32 v[116:117], v[126:127], v[114:115] op_sel_hi:[0,1]
	v_pk_mul_f32 v[114:115], v[126:127], v[122:123] op_sel_hi:[0,1]
	v_pk_mul_f32 v[122:123], v[142:143], v[128:129]
	v_lshlrev_b32_e32 v128, 16, v118
	v_and_b32_e32 v129, 0xffff0000, v118
	v_lshlrev_b32_e32 v118, 16, v119
	v_and_b32_e32 v119, 0xffff0000, v119
	v_pk_mul_f32 v[124:125], v[144:145], v[138:139]
	v_lshlrev_b32_e32 v138, 16, v120
	v_and_b32_e32 v139, 0xffff0000, v120
	v_lshlrev_b32_e32 v140, 16, v121
	v_and_b32_e32 v141, 0xffff0000, v121
	v_pk_mul_f32 v[128:129], v[146:147], v[128:129]
	v_pk_mul_f32 v[118:119], v[148:149], v[118:119]
	v_pk_mul_f32 v[138:139], v[150:151], v[138:139]
	v_pk_mul_f32 v[120:121], v[126:127], v[118:119] op_sel_hi:[0,1]
	v_pk_mul_f32 v[118:119], v[126:127], v[128:129] op_sel_hi:[0,1]
	v_pk_mul_f32 v[128:129], v[152:153], v[140:141]
	v_or_b32_e32 v1, s11, v1
	v_pk_mul_f32 v[124:125], v[126:127], v[124:125] op_sel_hi:[0,1]
	v_pk_mul_f32 v[122:123], v[126:127], v[122:123] op_sel_hi:[0,1]
	v_pk_mul_f32 v[128:129], v[126:127], v[128:129] op_sel_hi:[0,1]
	v_pk_mul_f32 v[126:127], v[126:127], v[138:139] op_sel_hi:[0,1]
	v_lshlrev_b32_e32 v138, 6, v1
	v_lshlrev_b32_e32 v139, 1, v158
	s_movk_i32 s11, 0x3c0
	v_lshlrev_b32_e32 v140, 2, v1
	v_and_or_b32 v138, v138, s11, v139
	v_and_b32_e32 v140, 32, v140
	v_bitop3_b32 v142, v138, s5, v140 bitop3:0xde
	v_lshlrev_b32_e32 v138, 6, v0
	v_and_or_b32 v138, v138, s11, v139
	v_lshlrev_b32_e32 v139, 2, v0
	v_and_b32_e32 v139, 32, v139
	v_bitop3_b32 v151, s15, v138, v139 bitop3:0xf6
	v_lshlrev_b32_e32 v138, 8, v0
	v_lshlrev_b32_e32 v141, 4, v157
	s_waitcnt vmcnt(6)
	v_and_b32_e32 v138, 0x18000, v138
	v_lshlrev_b32_e32 v140, 11, v156
	v_and_b32_e32 v141, 0x38000, v141
	v_or3_b32 v138, v154, v138, v140
	v_or3_b32 v140, v154, v141, v140
	s_ashr_i32 s57, s33, 31
	s_mov_b32 s19, 0x20000
	s_brev_b32 s18, -2
	s_and_b32 s17, s59, 0xffff
	s_mov_b32 s16, s58
	v_lshlrev_b32_e32 v152, 11, v1
	v_or_b32_e32 v153, s10, v158
	v_add_u32_e32 v138, v138, v155
	v_mov_b32_e32 v139, v133
	v_add_u32_e32 v140, v140, v155
	v_mov_b32_e32 v141, v133
	s_add_i32 s58, 0, 0x10000
	v_add_u32_e32 v154, 0, v142
	s_add_i32 s59, 0, 0x14000
	v_mov_b64_e32 v[142:143], 0xff
	v_mov_b64_e32 v[144:145], 0x100
	s_barrier
	s_branch .LBB0_509
